# barrier 7 (P6->P7) XCD-local when every workgroup sits on XCD bx%8 and grid=256 (launch-wide mismatch word, read once after barrier 1): leader skips L2 write-back + cross-XCD rendezvous
# speedup vs baseline: 1.0054x; 1.0038x over previous
; #define LAS __attribute__((address_space(3)))
; __device__ __forceinline__ unsigned xb_add(unsigned* p, unsigned v) { return __hip_atomic_fetch_add(p, v, __ATOMIC_RELAXED, __HIP_MEMORY_SCOPE_AGENT); }
; __device__ __forceinline__ unsigned xb_xcc_id() { return (unsigned)__builtin_amdgcn_s_getreg((3 << 11) | 20) & 0xFu; }
; __device__ __forceinline__ XcdBarrier xcd_barrier_post(unsigned* bar, volatile LAS unsigned* st) {
;     XcdBarrier b; b.bar = bar; b.x = xb_xcc_id(); b.st = st;
;     if (threadIdx.x == 0) (void)xb_add(&bar[XB_XCNT(b.x)], 1u);
;     return b;
; }
; __global__ void __launch_bounds__(512, 2) fwd_megakernel(Params P) {
;     extern __shared__ __attribute__((aligned(16))) unsigned char lds_raw[];
;     lds_t* lds = (lds_t*)lds_raw;
;     ...
;     const int G = gridDim.x, bx = (int)blockIdx.x;
;     unsigned char* ws = P.ws;
;     volatile LAS unsigned* misc = (volatile LAS unsigned*)(lds + 131072 + 512);
;     const int wave0 = __builtin_amdgcn_readfirstlane((int)threadIdx.x >> 6);
;     if (threadIdx.x < 2) misc[threadIdx.x] = 0u;
;     __syncthreads();
;     XcdBarrier bar = xcd_barrier_post((unsigned*)(ws + WS_BAR), misc); bar.w0 = wave0;
;     const bool subset = G >= 128;
;     const int NS2 = subset ? 16 : 0, NS4 = subset ? 64 : 0;
;     { FRESH_IDS; p0_prologue(P, lds, G, tid, wave, lane, true); }
_Z14fwd_megakernel6Params:
	s_load_dwordx2 s[68:69], s[0:1], 0x70
	s_load_dwordx4 s[60:63], s[0:1], 0x60
	s_load_dwordx8 s[4:11], s[0:1], 0x40
	s_load_dword s96, s[0:1], 0x78
	v_readfirstlane_b32 s3, v0
	v_cmp_gt_u32_e32 vcc, 2, v0
	s_waitcnt lgkmcnt(0)
	v_writelane_b32 v255, s4, 0
	s_nop 1
	v_writelane_b32 v255, s5, 1
	v_writelane_b32 v255, s6, 2
	v_writelane_b32 v255, s7, 3
	v_writelane_b32 v255, s8, 4
	v_writelane_b32 v255, s9, 5
	v_writelane_b32 v255, s10, 6
	v_writelane_b32 v255, s11, 7
	s_add_u32 s4, s0, 0x78
	s_addc_u32 s5, s1, 0
	v_writelane_b32 v255, s4, 8
	s_nop 1
	v_writelane_b32 v255, s5, 9
	v_writelane_b32 v255, s3, 10
	s_and_saveexec_b64 s[4:5], vcc
	v_lshl_add_u32 v1, v0, 2, 0
	v_add_u32_e32 v1, 0x20200, v1
	v_mov_b32_e32 v2, 0
	ds_write_b32 v1, v2
	s_or_b64 exec, exec, s[4:5]
	s_add_u32 s4, s68, 0x80000
	s_addc_u32 s5, s69, 0
	s_waitcnt lgkmcnt(0)
	s_barrier
	v_writelane_b32 v255, s4, 11
	s_getreg_b32 s3, hwreg(HW_REG_XCC_ID, 0, 4)
	s_and_b32 s33, s3, 15
	v_writelane_b32 v255, s5, 12
	v_cmp_eq_u32_e32 vcc, 0, v0
	s_and_saveexec_b64 s[4:5], vcc
	s_cbranch_execz .LBB0_5
	s_mov_b64 s[6:7], exec
	v_mbcnt_lo_u32_b32 v0, s6, 0
	v_mbcnt_hi_u32_b32 v0, s7, v0
	v_cmp_eq_u32_e32 vcc, 0, v0
	s_and_b64 s[8:9], exec, vcc
	s_mov_b64 exec, s[8:9]
	s_cbranch_execz .LBB0_5
	s_bcnt1_i32_b64 s6, s[6:7]
	s_lshl_b32 s3, s33, 8
	v_mov_b32_e32 v1, s6
	v_readlane_b32 s6, v255, 11
	v_mov_b32_e32 v0, s3
	v_readlane_b32 s7, v255, 12
	s_nop 4
	global_atomic_add v0, v1, s[6:7] offset:1024
	s_and_b32 s98, s2, 7
	s_cmp_lg_u32 s98, s33
	s_cbranch_scc1 .Lxm_bad
	s_cmp_eq_u32 s96, 0x100
	s_cbranch_scc1 .Lxm_ok
.Lxm_bad:
	v_mov_b32_e32 v0, 0x53000
	global_atomic_add v0, v1, s[68:69]
.Lxm_ok:
.LBB0_5:
	s_or_b64 exec, exec, s[4:5]
	s_load_dwordx16 s[36:51], s[0:1], 0x0
	v_readlane_b32 s1, v255, 10
	v_mbcnt_lo_u32_b32 v0, -1, 0
	s_and_b32 s97, s1, 0xffffffc0
	v_mbcnt_hi_u32_b32 v201, -1, v0
	s_lshr_b32 s0, s1, 6
	v_add_u32_e32 v175, s97, v201
	s_lshl_b32 s1, s2, 3
	v_mov_b32_e32 v28, v175
	v_writelane_b32 v255, s0, 13
	s_add_i32 s64, s0, s1
	s_lshl_b32 s66, s96, 3
	s_mov_b32 s5, 0
	v_writelane_b32 v255, s1, 14
	s_cmpk_gt_i32 s64, 0x77f
	v_and_b32_e32 v1, 63, v28
	s_cbranch_scc1 .LBB0_32
	s_waitcnt lgkmcnt(0)
	v_and_b32_e32 v123, 7, v201
	v_lshrrev_b32_e32 v122, 3, v201
	v_lshlrev_b32_e32 v124, 5, v122
	s_cmpk_lt_u32 s64, 0x580
	s_cbranch_scc0 .Lp0w_wout
	s_mul_i32 s0, s64, 0x2e9
	s_lshr_b32 s0, s0, 16
	s_mul_i32 s1, s0, 0x58
	s_sub_u32 s1, s64, s1
	s_lshl_b32 s3, s1, 5
	s_mov_b32 s15, 1.0
	s_cmpk_lt_u32 s3, 0x200
	s_cselect_b32 s15, 0x3e000000, s15
	s_sub_u32 s4, s3, 0x500
	s_cmpk_lt_u32 s4, 0x200
	s_cselect_b32 s15, 0x3db504f3, s15
	s_and_b32 s17, s3, 0xff
	s_lshr_b32 s18, s17, 7
	s_lshl_b32 s18, s18, 7
	s_bfe_u32 s19, s17, 0x10005
	s_lshl_b32 s19, s19, 6
	s_add_u32 s18, s18, s19
	s_bfe_u32 s19, s17, 0x10006
	s_lshl_b32 s19, s19, 5
	s_add_u32 s18, s18, s19
	s_andn2_b32 s19, s3, 0xff
	s_add_u32 s18, s18, s19
	s_sub_u32 s4, s3, 0x300
	s_cmpk_lt_u32 s4, 0x400
	s_cselect_b32 s3, s18, s3
	s_mul_i32 s4, s0, 0xb0000
	s_lshl_b32 s17, s1, 7
	s_add_u32 s4, s4, s17
	s_add_u32 s6, s48, s4
	s_addc_u32 s7, s49, 0
	s_lshl_b32 s4, s3, 11
	s_lshl_b32 s17, s0, 7
	s_add_u32 s4, s4, s17
	s_add_u32 s4, s4, 0x200000
	s_add_u32 s8, s68, s4
	s_addc_u32 s9, s69, 0
	s_movk_i32 s12, 0x2c00
	s_mov_b32 s14, 1
	s_branch .Lp0w_common

;     __host__ __device__ void init(int M, int N, int K, int G_, int c_, int tailM_, int nsplit_) { so.init(M, N, K, G_, c_); tailM = tailM_; nsplit = nsplit_; npieces = tailM_ * so.nN * nsplit_; }
;     __host__ __device__ bool next(int i, Unit& u) const { if (i != 0 || c >= cnt) return false; u.pm = pm0 + c / nN; u.pn = c % nN; u.k0 = 0; u.nt = ntk; return true; }
;     __host__ __device__ bool next(int i, Unit& u) const { return at((long)i * G + c, u); }
;     __host__ __device__ bool at(long L, Unit& u) const {
;         if (L >= nwg) return false;
;         int wgid = (int)L; { const int q = nwg / NXCD, r = nwg % NXCD, xcd = wgid % NXCD, off = wgid / NXCD; wgid = (xcd < r ? xcd * (q + 1) : r * (q + 1) + (xcd - r) * q) + off; }
; __global__ void __launch_bounds__(512, 2) fwd_megakernel(Params P) {
;     ...
;     xcd_barrier(bar);
;     {
;         pg8::Gemm g{(const bf16_t*)(ws + WS_XN), (const bf16_t*)(ws + WS_WIN), MT, INW, DM}; pg8::StaticOrder S; S.init(MT, INW, DM, G, bx);
;         pg8::EpiInProj E{(bf16_t*)(ws + WS_Z), (const float*)(ws + WS_RS1), P.out};
;         pg8::gemm_phase<pg8::EpiInProj, pg8::StaticOrder, true, true>(lds, g, S, E, wave0);
.LBB0_100:
	s_or_b64 exec, exec, s[0:1]
	s_cmpk_lt_i32 s2, 0x2ec
	v_mov_b32_e32 v8, v175
	s_cselect_b64 s[0:1], -1, 0
	s_cmpk_gt_i32 s2, 0x2eb
	s_waitcnt lgkmcnt(0)
	s_barrier
	s_load_dword s100, s[68:69], 0x53000
	s_waitcnt lgkmcnt(0)
	s_cbranch_scc1 .LBB0_106
	s_ashr_i32 s3, s2, 31
	s_lshr_b32 s3, s3, 29
	s_add_i32 s3, s2, s3
	s_and_b32 s4, s3, -8
	s_sub_i32 s6, s2, s4
	s_cmp_gt_i32 s6, 3
	s_cbranch_scc0 .LBB0_103
	s_mul_i32 s4, s6, 0x5d
	s_add_i32 s7, s4, 4
	s_cbranch_execz .LBB0_104
	s_branch .LBB0_105

; __device__ __forceinline__ unsigned xb_ld(unsigned* p)              { return __hip_atomic_load(p, __ATOMIC_RELAXED, __HIP_MEMORY_SCOPE_AGENT); }
; __device__ __forceinline__ unsigned xb_add(unsigned* p, unsigned v) { return __hip_atomic_fetch_add(p, v, __ATOMIC_RELAXED, __HIP_MEMORY_SCOPE_AGENT); }
; #define XB_SPIN(cond, bar) do { unsigned _sp = 0; while (cond) { __builtin_amdgcn_s_sleep(1); \
;     if ((++_sp & 255u) == 0u) { if (xb_ld(&(bar)[XB_TMO])) break; if (_sp > XB_SPIN_CAP) { atomicAdd(&(bar)[XB_TMO], 1u); break; } } } } while (0)
; __device__ __forceinline__ void xcd_barrier(const XcdBarrier& b) {
;     ...
;         const unsigned old = xb_add(&bar[XB_XSUB(b.x)], 1u);
;         const unsigned gen = old / nloc;
;         if (old + 1u == (gen + 1u) * nloc) {
;             __builtin_amdgcn_fence(__ATOMIC_RELEASE, "agent");
;             asm volatile("s_waitcnt vmcnt(0)" ::: "memory");
;             const unsigned og = xb_add(&bar[XB_TOP], 1u);
;             const unsigned tg = og / nx;
;             if (og + 1u == (tg + 1u) * nx) xb_add(&bar[XB_TOPGEN], 1u);
;             else XB_SPIN(xb_ld(&bar[XB_TOPGEN]) == tg, bar);
;             __builtin_amdgcn_fence(__ATOMIC_ACQUIRE, "agent");
;             xb_add(&bar[XB_XGEN(b.x)], 1u);
;             asm volatile("s_waitcnt vmcnt(0)" ::: "memory");
.LBB0_1016:
	s_andn2_saveexec_b64 s[12:13], s[12:13]
	s_cbranch_execz .LBB0_1036
	s_mov_b64 s[12:13], exec
	buffer_inv sc1
	s_cmp_eq_u32 s100, 0
	s_cbranch_scc1 .LBB0_1033
	buffer_wbl2 sc1
	s_waitcnt lgkmcnt(0)
	s_waitcnt vmcnt(0)
	v_mbcnt_lo_u32_b32 v1, s12, 0
	v_mbcnt_hi_u32_b32 v1, s13, v1
	v_cmp_eq_u32_e32 vcc, 0, v1
	s_and_saveexec_b64 s[14:15], vcc
	s_cbranch_execz .LBB0_1019
	s_bcnt1_i32_b64 s3, s[12:13]
	v_mov_b32_e32 v2, 0x83000
	v_mov_b32_e32 v3, s3
	global_atomic_add v2, v2, v3, s[68:69] offset:1024 sc0
